# k11 + attention region: packed f32 VALU ops (v_pk_add/mul_f32) beside the MFMAs split into scalar f32 ops (same arithmetic)
# baseline (speedup 1.0000x reference)
.LBB0_1310:
	s_or_b64 exec, exec, s[6:7]
	s_and_b32 s43, s41, 3
	s_lshr_b32 s40, s37, 5
	s_xor_b32 s60, s43, 7
	s_ashr_i32 s5, s4, 31
	s_mul_hi_i32 s6, s8, 0x180000
	s_mul_i32 s8, s8, 0x180000
	s_add_u32 s61, s48, s8
	s_addc_u32 s66, s49, s6
	s_lshl_b32 s13, s12, 6
	s_lshl_b32 s6, s12, 7
	v_cmp_gt_u32_e32 vcc, 32, v7
	s_add_u32 s8, s61, s6
	s_addc_u32 s9, s66, 0
	v_cndmask_b32_e32 v0, v9, v0, vcc
	v_add_f32_e32 v0, v0, v10
	s_add_u32 s6, s8, 0x80000
	v_sub_f32_e32 v0, v0, v5
	s_addc_u32 s7, s9, 0
	v_add_f32_e32 v2, v2, v0
	v_add_f32_e32 v3, v3, v0
	v_add_f32_e32 v4, v4, v0
	v_add_f32_e32 v5, v5, v0
	v_lshl_add_u32 v0, v6, 4, 0
	s_add_u32 s8, s8, 0xc0000
	v_mul_f32_e32 v4, s44, v4
	v_mul_f32_e32 v5, s44, v5
	v_mul_f32_e32 v2, s44, v2
	v_mul_f32_e32 v3, s44, v3
	v_add_u32_e32 v0, 0x14800, v0
	s_addc_u32 s9, s9, 0
	s_lshl_b64 s[10:11], s[4:5], 11
	s_lshl_b32 s4, s12, 2
	ds_write_b128 v0, v[2:5]
	s_add_u32 s2, s2, s4
	s_waitcnt lgkmcnt(0)
	s_barrier
	s_addc_u32 s3, s3, 0
	s_add_u32 s67, s2, 0xf900000
	s_addc_u32 s68, s3, 0
	s_mov_b64 s[4:5], -1
	s_lshl_b32 s69, s13, 1
	s_branch .LBB0_1312

.LBB0_1312:
	s_and_b64 s[2:3], s[4:5], exec
	s_mov_b32 s2, s33
	s_mov_b32 s3, -1
	s_cselect_b32 s24, s43, s60
	v_mbcnt_lo_u32_b32 v0, s3, 0
	v_mbcnt_hi_u32_b32 v0, s3, v0
	v_lshl_or_b32 v216, s2, 6, v0
	s_mul_i32 s2, s24, 0x180000
	v_readfirstlane_b32 s17, v216
	s_ashr_i32 s70, s17, 6
	s_add_u32 s12, s61, s2
	s_addc_u32 s13, s66, 0
	s_lshl_b32 s14, s70, 5
	s_ashr_i32 s15, s14, 31
	s_lshl_b64 s[2:3], s[14:15], 11
	s_add_u32 s2, s12, s2
	s_addc_u32 s3, s13, s3
	v_and_b32_e32 v217, 63, v216
	s_add_u32 s12, s2, s69
	s_addc_u32 s13, s3, 0
	v_lshlrev_b32_e32 v0, 10, v217
	s_lshl_b32 s2, s70, 3
	s_waitcnt lgkmcnt(0)
	v_lshl_add_u64 v[2:3], s[6:7], 0, v[0:1]
	s_ashr_i32 s3, s2, 31
	v_lshl_add_u64 v[212:213], s[2:3], 1, v[2:3]
	s_lshl_b32 s2, s70, 4
	v_bfe_u32 v0, v216, 2, 4
	v_and_or_b32 v0, s2, 48, v0
	s_ashr_i32 s2, s17, 3
	s_andn2_b32 s2, s2, 31
	v_lshlrev_b32_e32 v0, 10, v0
	s_ashr_i32 s3, s2, 31
	s_lshl_b32 s16, s70, 10
	v_lshl_add_u64 v[2:3], s[8:9], 0, v[0:1]
	v_lshlrev_b32_e32 v0, 3, v216
	s_cmp_lg_u32 0, -1
	v_lshl_add_u64 v[2:3], s[2:3], 1, v[2:3]
	v_and_b32_e32 v220, 24, v0
	s_cselect_b32 s2, 0, 0
	v_lshlrev_b32_e32 v0, 1, v220
	s_add_i32 s74, s16, s2
	s_mov_b32 s2, m0
	s_mov_b32 m0, s74
	s_nop 0
	global_load_lds_dwordx4 v[212:213], off
	s_mov_b32 m0, s2
	v_bfe_u32 v219, v216, 5, 1
	v_lshl_add_u64 v[214:215], v[2:3], 0, v[0:1]
	s_add_i32 s75, s74, 0x6000
	s_mov_b32 s2, m0
	s_mov_b32 m0, s75
	s_nop 0
	global_load_lds_dwordx4 v[214:215], off
	s_mov_b32 m0, s2
	v_lshl_add_u64 v[2:3], v[212:213], 0, s[30:31]
	v_and_b32_e32 v218, 31, v216
	s_add_i32 s2, s74, 0x2000
	s_mov_b32 s3, m0
	s_mov_b32 m0, s2
	s_nop 0
	global_load_lds_dwordx4 v[2:3], off
	s_mov_b32 m0, s3
	v_lshlrev_b32_e32 v2, 4, v219
	v_lshl_or_b32 v3, v218, 11, v2
	global_load_dwordx4 v[140:143], v3, s[12:13] sc1
	global_load_dwordx4 v[136:139], v3, s[12:13] offset:32 sc1
	global_load_dwordx4 v[132:135], v3, s[12:13] offset:64 sc1
	global_load_dwordx4 v[128:131], v3, s[12:13] offset:96 sc1
	v_lshlrev_b32_e32 v0, 10, v219
	v_lshlrev_b32_e32 v4, 4, v218
	v_add_u32_e32 v2, 0, v2
	v_mov_b32_e32 v14, v1
	v_mov_b32_e32 v15, v1
	v_add_u32_e32 v225, 0x14800, v2
	v_add3_u32 v228, 0, v0, v4
	v_mov_b32_e32 v0, v1
	v_mov_b32_e32 v2, v1
	v_mov_b32_e32 v3, v1
	v_mov_b32_e32 v4, v1
	v_mov_b32_e32 v5, v1
	v_mov_b32_e32 v6, v1
	v_mov_b32_e32 v7, v1
	v_mov_b32_e32 v8, v1
	v_mov_b32_e32 v9, v1
	v_mov_b32_e32 v10, v1
	v_mov_b32_e32 v11, v1
	v_mov_b32_e32 v12, v1
	v_mov_b32_e32 v13, v1
	v_mov_b64_e32 v[32:33], v[14:15]
	v_mov_b64_e32 v[30:31], v[12:13]
	v_mov_b64_e32 v[28:29], v[10:11]
	v_mov_b64_e32 v[26:27], v[8:9]
	v_mov_b64_e32 v[24:25], v[6:7]
	v_mov_b64_e32 v[22:23], v[4:5]
	v_mov_b64_e32 v[20:21], v[2:3]
	v_mov_b64_e32 v[18:19], v[0:1]
	v_lshl_add_u64 v[2:3], v[212:213], 0, s[90:91]
	s_add_i32 s2, s74, 0x4000
	s_mov_b32 s3, m0
	s_mov_b32 m0, s2
	s_nop 0
	global_load_lds_dwordx4 v[2:3], off
	s_mov_b32 m0, s3
	s_waitcnt vmcnt(3) lgkmcnt(0)
	s_barrier
	ds_read_b128 v[34:37], v228 offset:512
	ds_read_b128 v[38:41], v228
	s_cmp_lg_u32 s24, 0
	s_cselect_b64 s[2:3], -1, 0
	v_lshlrev_b32_e32 v221, 2, v219
	v_or_b32_e32 v227, s14, v218
	s_and_b64 vcc, exec, s[2:3]
	s_waitcnt vmcnt(3) lgkmcnt(0)
	v_mfma_f32_32x32x16_bf16 v[2:17], v[38:41], v[140:143], v[18:33]
	v_mfma_f32_32x32x16_bf16 v[18:33], v[34:37], v[140:143], v[18:33]
	ds_read_b128 v[34:37], v228 offset:2560
	ds_read_b128 v[38:41], v228 offset:2048
	s_waitcnt vmcnt(2) lgkmcnt(0)
	v_mfma_f32_32x32x16_bf16 v[2:17], v[38:41], v[136:139], v[2:17]
	v_mfma_f32_32x32x16_bf16 v[18:33], v[34:37], v[136:139], v[18:33]
	ds_read_b128 v[34:37], v228 offset:4608
	ds_read_b128 v[38:41], v228 offset:4096
	s_waitcnt vmcnt(1) lgkmcnt(0)
	v_mfma_f32_32x32x16_bf16 v[2:17], v[38:41], v[132:135], v[2:17]
	v_mfma_f32_32x32x16_bf16 v[18:33], v[34:37], v[132:135], v[18:33]
	ds_read_b128 v[34:37], v228 offset:6656
	ds_read_b128 v[38:41], v228 offset:6144
	s_waitcnt vmcnt(0) lgkmcnt(0)
	v_mfma_f32_32x32x16_bf16 v[2:17], v[38:41], v[128:131], v[2:17]
	v_mfma_f32_32x32x16_bf16 v[18:33], v[34:37], v[128:131], v[18:33]
	s_nop 15
	s_nop 7
	ds_read_b128 v[34:37], v225
	ds_read_b128 v[38:41], v225 offset:32
	ds_read_b128 v[42:45], v225 offset:128
	s_waitcnt lgkmcnt(2)
	s_nop 6
	v_add_f32_e32 v2, v34, v2
	v_add_f32_e32 v3, v35, v3
	v_add_f32_e32 v4, v36, v4
	v_add_f32_e32 v5, v37, v5
	ds_read_b128 v[34:37], v225 offset:160
	s_waitcnt lgkmcnt(2)
	v_add_f32_e32 v6, v6, v38
	v_add_f32_e32 v7, v7, v39
	v_add_f32_e32 v8, v8, v40
	v_add_f32_e32 v9, v9, v41
	ds_read_b128 v[38:41], v225 offset:64
	ds_read_b128 v[46:49], v225 offset:192
	s_waitcnt lgkmcnt(3)
	v_add_f32_e32 v20, v20, v44
	v_add_f32_e32 v21, v21, v45
	s_waitcnt lgkmcnt(2)
	v_add_f32_e32 v22, v22, v34
	v_add_f32_e32 v23, v23, v35
	v_add_f32_e32 v24, v24, v36
	v_add_f32_e32 v25, v25, v37
	s_waitcnt lgkmcnt(1)
	v_add_f32_e32 v10, v10, v38
	v_add_f32_e32 v11, v11, v39
	v_add_f32_e32 v12, v12, v40
	v_add_f32_e32 v13, v13, v41
	ds_read_b128 v[38:41], v225 offset:96
	ds_read_b128 v[50:53], v225 offset:224
	s_waitcnt lgkmcnt(2)
	v_add_f32_e32 v26, v26, v46
	v_add_f32_e32 v27, v27, v47
	v_add_f32_e32 v28, v28, v48
	v_add_f32_e32 v29, v29, v49
	v_add_f32_e32 v18, v18, v42
	v_add_f32_e32 v19, v19, v43
	s_waitcnt lgkmcnt(1)
	v_add_f32_e32 v14, v14, v38
	v_add_f32_e32 v15, v15, v39
	v_add_f32_e32 v16, v16, v40
	v_add_f32_e32 v17, v17, v41
	s_waitcnt lgkmcnt(0)
	v_add_f32_e32 v30, v30, v50
	v_add_f32_e32 v31, v31, v51
	v_add_f32_e32 v32, v32, v52
	v_add_f32_e32 v33, v33, v53
	s_nop 0
	s_nop 3
	s_cbranch_vccnz .LBB0_1314
	v_or_b32_e32 v0, 32, v221
	v_cmp_le_i32_e32 vcc, v0, v227
	v_or_b32_e32 v0, 33, v221
	s_nop 0
	v_cndmask_b32_e32 v18, v238, v18, vcc
	v_cmp_lt_i32_e32 vcc, v221, v227
	s_nop 1
	v_cndmask_b32_e32 v3, v238, v3, vcc
	v_cmp_le_i32_e32 vcc, v221, v227
	s_nop 1
	v_cndmask_b32_e32 v2, v238, v2, vcc
	v_cmp_le_i32_e32 vcc, v0, v227
	v_or_b32_e32 v0, 2, v221
	s_nop 0
	v_cndmask_b32_e32 v19, v238, v19, vcc
	v_cmp_le_i32_e32 vcc, v0, v227
	v_or_b32_e32 v0, 34, v221
	s_nop 0
	v_cndmask_b32_e32 v4, v238, v4, vcc
	v_cmp_le_i32_e32 vcc, v0, v227
	v_or_b32_e32 v0, 3, v221
	s_nop 0
	v_cndmask_b32_e32 v20, v238, v20, vcc
	v_cmp_le_i32_e32 vcc, v0, v227
	v_or_b32_e32 v0, 35, v221
	s_nop 0
	v_cndmask_b32_e32 v5, v238, v5, vcc
	v_cmp_le_i32_e32 vcc, v0, v227
	v_or_b32_e32 v0, 8, v221
	s_nop 0
	v_cndmask_b32_e32 v21, v238, v21, vcc
	v_cmp_le_i32_e32 vcc, v0, v227
	v_or_b32_e32 v0, 40, v221
	s_nop 0
	v_cndmask_b32_e32 v6, v238, v6, vcc
	v_cmp_le_i32_e32 vcc, v0, v227
	v_or_b32_e32 v0, 9, v221
	s_nop 0
	v_cndmask_b32_e32 v22, v238, v22, vcc
	v_cmp_le_i32_e32 vcc, v0, v227
	v_or_b32_e32 v0, 41, v221
	s_nop 0
	v_cndmask_b32_e32 v7, v238, v7, vcc
	v_cmp_le_i32_e32 vcc, v0, v227
	v_or_b32_e32 v0, 10, v221
	s_nop 0
	v_cndmask_b32_e32 v23, v238, v23, vcc
	v_cmp_le_i32_e32 vcc, v0, v227
	v_or_b32_e32 v0, 42, v221
	s_nop 0
	v_cndmask_b32_e32 v8, v238, v8, vcc
	v_cmp_le_i32_e32 vcc, v0, v227
	v_or_b32_e32 v0, 11, v221
	s_nop 0
	v_cndmask_b32_e32 v24, v238, v24, vcc
	v_cmp_le_i32_e32 vcc, v0, v227
	v_or_b32_e32 v0, 43, v221
	s_nop 0
	v_cndmask_b32_e32 v9, v238, v9, vcc
	v_cmp_le_i32_e32 vcc, v0, v227
	v_or_b32_e32 v0, 16, v221
	s_nop 0
	v_cndmask_b32_e32 v25, v238, v25, vcc
	v_cmp_le_i32_e32 vcc, v0, v227
	v_or_b32_e32 v0, 48, v221
	s_nop 0
	v_cndmask_b32_e32 v10, v238, v10, vcc
	v_cmp_le_i32_e32 vcc, v0, v227
	v_or_b32_e32 v0, 17, v221
	s_nop 0
	v_cndmask_b32_e32 v26, v238, v26, vcc
	v_cmp_le_i32_e32 vcc, v0, v227
	v_or_b32_e32 v0, 49, v221
	s_nop 0
	v_cndmask_b32_e32 v11, v238, v11, vcc
	v_cmp_le_i32_e32 vcc, v0, v227
	v_or_b32_e32 v0, 18, v221
	s_nop 0
	v_cndmask_b32_e32 v27, v238, v27, vcc
	v_cmp_le_i32_e32 vcc, v0, v227
	v_or_b32_e32 v0, 50, v221
	s_nop 0
	v_cndmask_b32_e32 v12, v238, v12, vcc
	v_cmp_le_i32_e32 vcc, v0, v227
	v_or_b32_e32 v0, 19, v221
	s_nop 0
	v_cndmask_b32_e32 v28, v238, v28, vcc
	v_cmp_le_i32_e32 vcc, v0, v227
	v_or_b32_e32 v0, 51, v221
	s_nop 0
	v_cndmask_b32_e32 v13, v238, v13, vcc
	v_cmp_le_i32_e32 vcc, v0, v227
	v_or_b32_e32 v0, 24, v221
	s_nop 0
	v_cndmask_b32_e32 v29, v238, v29, vcc
	v_cmp_le_i32_e32 vcc, v0, v227
	v_or_b32_e32 v0, 56, v221
	s_nop 0
	v_cndmask_b32_e32 v14, v238, v14, vcc
	v_cmp_le_i32_e32 vcc, v0, v227
	v_or_b32_e32 v0, 25, v221
	s_nop 0
	v_cndmask_b32_e32 v30, v238, v30, vcc
	v_cmp_le_i32_e32 vcc, v0, v227
	v_or_b32_e32 v0, 57, v221
	s_nop 0
	v_cndmask_b32_e32 v15, v238, v15, vcc
	v_cmp_le_i32_e32 vcc, v0, v227
	v_or_b32_e32 v0, 26, v221
	s_nop 0
	v_cndmask_b32_e32 v31, v238, v31, vcc
	v_cmp_le_i32_e32 vcc, v0, v227
	v_or_b32_e32 v0, 58, v221
	s_nop 0
	v_cndmask_b32_e32 v16, v238, v16, vcc
	v_cmp_le_i32_e32 vcc, v0, v227
	v_or_b32_e32 v0, 27, v221
	s_nop 0
	v_cndmask_b32_e32 v32, v238, v32, vcc
	v_cmp_le_i32_e32 vcc, v0, v227
	v_or_b32_e32 v0, 59, v221
	s_nop 0
	v_cndmask_b32_e32 v17, v238, v17, vcc
	v_cmp_le_i32_e32 vcc, v0, v227
	s_nop 1
	v_cndmask_b32_e32 v33, v238, v33, vcc

.LBB0_1316:
	v_add_u32_e32 v0, s16, v240
	ds_read_b64_tr_b16 v[192:193], v0 offset:24576
	ds_read_b64_tr_b16 v[194:195], v0 offset:25088
	v_add_f32_e32 v2, v80, v81
	v_add_f32_e32 v2, v82, v2
	v_add_f32_e32 v2, v83, v2
	v_add_f32_e32 v2, v84, v2
	v_add_f32_e32 v2, v85, v2
	v_cvt_pk_bf16_f32 v156, v80, v81
	v_cvt_pk_bf16_f32 v157, v82, v83
	s_waitcnt lgkmcnt(9)
	v_mfma_f32_32x32x16_bf16 v[96:111], v[188:191], v[140:143], v[48:63]
	ds_read_b64_tr_b16 v[188:189], v0 offset:28672
	ds_read_b64_tr_b16 v[190:191], v0 offset:29184
	v_add_f32_e32 v2, v86, v2
	v_add_f32_e32 v2, v87, v2
	v_add_f32_e32 v2, v88, v2
	v_add_f32_e32 v2, v89, v2
	v_cvt_pk_bf16_f32 v158, v84, v85
	v_cvt_pk_bf16_f32 v159, v86, v87
	s_waitcnt lgkmcnt(10)
	v_mfma_f32_32x32x16_bf16 v[112:127], v[184:187], v[140:143], v[48:63]
	ds_read_b64_tr_b16 v[10:11], v0 offset:25600
	ds_read_b64_tr_b16 v[12:13], v0 offset:26112
	v_add_f32_e32 v2, v90, v2
	v_add_f32_e32 v2, v91, v2
	v_add_f32_e32 v2, v92, v2
	v_add_f32_e32 v2, v93, v2
	v_cvt_pk_bf16_f32 v152, v88, v89
	v_cvt_pk_bf16_f32 v153, v90, v91
	s_waitcnt lgkmcnt(11)
	v_mfma_f32_32x32x16_bf16 v[96:111], v[180:183], v[136:139], v[96:111]
	ds_read_b64_tr_b16 v[180:181], v0 offset:29696
	ds_read_b64_tr_b16 v[182:183], v0 offset:30208
	v_add_f32_e32 v2, v94, v2
	v_add_f32_e32 v2, v95, v2
	v_add_f32_e32 v2, v64, v2
	v_add_f32_e32 v2, v65, v2
	v_cvt_pk_bf16_f32 v154, v92, v93
	v_cvt_pk_bf16_f32 v155, v94, v95
	s_waitcnt lgkmcnt(12)
	v_mfma_f32_32x32x16_bf16 v[112:127], v[176:179], v[136:139], v[112:127]
	ds_read_b64_tr_b16 v[176:177], v0 offset:26624
	ds_read_b64_tr_b16 v[178:179], v0 offset:27136
	v_add_f32_e32 v2, v66, v2
	v_add_f32_e32 v2, v67, v2
	v_add_f32_e32 v2, v68, v2
	v_add_f32_e32 v6, v69, v2
	v_cvt_pk_bf16_f32 v148, v64, v65
	v_cvt_pk_bf16_f32 v149, v66, v67
	s_waitcnt lgkmcnt(13)
	v_mfma_f32_32x32x16_bf16 v[96:111], v[172:175], v[132:135], v[96:111]
	ds_read_b64_tr_b16 v[2:3], v0 offset:30720
	ds_read_b64_tr_b16 v[4:5], v0 offset:31232
	v_add_f32_e32 v6, v70, v6
	v_add_f32_e32 v6, v71, v6
	v_add_f32_e32 v6, v72, v6
	v_add_f32_e32 v14, v73, v6
	v_cvt_pk_bf16_f32 v150, v68, v69
	v_cvt_pk_bf16_f32 v151, v70, v71
	s_waitcnt lgkmcnt(14)
	v_mfma_f32_32x32x16_bf16 v[112:127], v[168:171], v[132:135], v[112:127]
	ds_read_b64_tr_b16 v[6:7], v0 offset:27648
	ds_read_b64_tr_b16 v[8:9], v0 offset:28160
	v_add_f32_e32 v14, v74, v14
	v_add_f32_e32 v14, v75, v14
	v_add_f32_e32 v14, v76, v14
	v_add_f32_e32 v14, v77, v14
	v_cvt_pk_bf16_f32 v144, v72, v73
	v_cvt_pk_bf16_f32 v145, v74, v75
	s_waitcnt lgkmcnt(14)
	v_mfma_f32_32x32x16_bf16 v[96:111], v[164:167], v[128:131], v[96:111]
	ds_read_b64_tr_b16 v[164:165], v0 offset:31744
	ds_read_b64_tr_b16 v[166:167], v0 offset:32256
	v_add_f32_e32 v0, v78, v14
	v_add_f32_e32 v0, v79, v0
	v_add_f32_e32 v0, 0, v0
	v_cvt_pk_bf16_f32 v146, v76, v77
	v_cvt_pk_bf16_f32 v147, v78, v79
	v_mfma_f32_32x32x16_bf16 v[112:127], v[160:163], v[128:131], v[112:127]
	s_add_i32 s16, s46, -2
	s_lshr_b32 s16, s16, 2
	s_and_b32 s22, s47, 0x18000
	v_mad_u64_u32 v[14:15], s[16:17], s16, v239, v[212:213]
	s_lshl_b32 s26, s22, 1
	v_lshl_add_u64 v[14:15], v[14:15], 0, s[26:27]
	s_add_i32 s16, s50, s74
	s_mov_b32 s17, m0
	s_mov_b32 m0, s16
	s_nop 0
	global_load_lds_dwordx4 v[14:15], off
	s_mov_b32 m0, s17
	s_add_i32 s16, s46, -4
	s_add_i32 s17, s47, 0xffff0000
	s_lshr_b32 s16, s16, 2
	s_and_b32 s22, s17, 0x18000
	v_mad_u64_u32 v[14:15], s[16:17], s16, v239, v[214:215]
	s_lshl_b32 s26, s22, 1
	v_lshl_add_u64 v[14:15], v[14:15], 0, s[26:27]
	s_add_i32 s16, s25, s75
	s_mov_b32 s17, m0
	s_mov_b32 m0, s16
	s_nop 0
	global_load_lds_dwordx4 v[14:15], off
	s_mov_b32 m0, s17
	ds_read_b128 v[64:67], v200
	ds_read_b128 v[68:71], v200 offset:32
	ds_read_b128 v[72:75], v200 offset:128
	v_add_f32_e32 v0, v241, v0
	s_waitcnt lgkmcnt(2)
	v_add_f32_e32 v82, v98, v66
	v_add_f32_e32 v83, v99, v67
	s_waitcnt lgkmcnt(1)
	v_add_f32_e32 v84, v100, v68
	v_add_f32_e32 v85, v101, v69
	s_waitcnt lgkmcnt(0)
	v_add_f32_e32 v14, v112, v72
	v_add_f32_e32 v15, v113, v73
	v_add_f32_e32 v66, v114, v74
	v_add_f32_e32 v67, v115, v75
	ds_read_b128 v[72:75], v200 offset:160
	v_add_f32_e32 v86, v102, v70
	v_add_f32_e32 v87, v103, v71
	v_add_f32_e32 v64, v96, v64
	v_add_f32_e32 v65, v97, v65
	v_max3_f32 v81, v82, v83, v15
	v_max_f32_e32 v80, v64, v65
	s_waitcnt lgkmcnt(0)
	v_add_f32_e32 v68, v116, v72
	v_add_f32_e32 v69, v117, v73
	v_add_f32_e32 v70, v118, v74
	v_add_f32_e32 v71, v119, v75
	ds_read_b128 v[72:75], v200 offset:64
	ds_read_b128 v[76:79], v200 offset:192
	v_max3_f32 v80, v80, v14, v66
	v_max3_f32 v80, v80, v67, v84
	v_max3_f32 v81, v81, v86, v87
	s_waitcnt lgkmcnt(1)
	v_add_f32_e32 v88, v104, v72
	v_add_f32_e32 v89, v105, v73
	s_waitcnt lgkmcnt(0)
	v_add_f32_e32 v72, v120, v76
	v_add_f32_e32 v73, v121, v77
	v_add_f32_e32 v90, v106, v74
	v_add_f32_e32 v91, v107, v75
	v_add_f32_e32 v74, v122, v78
	v_add_f32_e32 v75, v123, v79
	ds_read_b128 v[76:79], v200 offset:96
	ds_read_b128 v[94:97], v200 offset:224
	v_max3_f32 v80, v80, v85, v68
	v_max3_f32 v81, v81, v70, v71
	v_max3_f32 v80, v80, v69, v88
	v_max3_f32 v81, v81, v90, v91
	s_waitcnt lgkmcnt(1)
	v_add_f32_e32 v92, v108, v76
	v_add_f32_e32 v93, v109, v77
	s_waitcnt lgkmcnt(0)
	v_add_f32_e32 v76, v124, v94
	v_add_f32_e32 v77, v125, v95
	v_add_f32_e32 v94, v110, v78
	v_add_f32_e32 v95, v111, v79
	v_max3_f32 v80, v80, v89, v72
	v_max3_f32 v81, v81, v74, v75
	v_add_f32_e32 v78, v126, v96
	v_add_f32_e32 v79, v127, v97
	v_max3_f32 v80, v80, v73, v92
	v_max3_f32 v81, v81, v94, v95
	v_max3_f32 v80, v80, v93, v76
	v_max3_f32 v81, v81, v78, v79
	v_max3_f32 v80, v80, v77, v81
	v_mov_b32_e32 v81, v80
	s_nop 1
	v_permlane32_swap_b32_e32 v80, v81
	v_max_f32_e32 v81, v81, v81
	v_max_f32_e32 v80, v80, v80
	v_max_f32_e32 v80, v80, v81
	v_cmp_lt_f32_e32 vcc, s36, v80
	s_cmp_lg_u64 vcc, 0
	s_cselect_b64 s[16:17], -1, 0
	s_cbranch_vccnz .LBB0_1324
.LBB0_1317:
	v_mfma_f32_32x32x16_bf16 v[32:47], v[156:159], v[192:195], v[32:47]
	v_exp_f32_e32 v80, v64
	v_exp_f32_e32 v81, v65
	v_exp_f32_e32 v82, v82
	v_exp_f32_e32 v83, v83
	v_mfma_f32_32x32x16_bf16 v[16:31], v[156:159], v[188:191], v[16:31]
	v_exp_f32_e32 v84, v84
	v_exp_f32_e32 v85, v85
	v_exp_f32_e32 v86, v86
	v_exp_f32_e32 v87, v87
	v_add_u32_e32 v96, s25, v228
	ds_read_b128 v[112:115], v96
	ds_read_b128 v[160:163], v96 offset:512
	v_mfma_f32_32x32x16_bf16 v[32:47], v[152:155], v[10:13], v[32:47]
	v_exp_f32_e32 v88, v88
	v_exp_f32_e32 v89, v89
	v_exp_f32_e32 v90, v90
	v_exp_f32_e32 v91, v91
	ds_read_b128 v[192:195], v96 offset:2048
	ds_read_b128 v[188:191], v96 offset:2560
	v_mfma_f32_32x32x16_bf16 v[16:31], v[152:155], v[180:183], v[16:31]
	v_exp_f32_e32 v92, v92
	v_exp_f32_e32 v93, v93
	v_exp_f32_e32 v94, v94
	v_exp_f32_e32 v95, v95
	ds_read_b128 v[184:187], v96 offset:4096
	ds_read_b128 v[180:183], v96 offset:4608
	v_mfma_f32_32x32x16_bf16 v[32:47], v[148:151], v[176:179], v[32:47]
	v_exp_f32_e32 v64, v14
	v_exp_f32_e32 v65, v15
	v_exp_f32_e32 v66, v66
	v_exp_f32_e32 v67, v67
	ds_read_b128 v[176:179], v96 offset:6144
	ds_read_b128 v[172:175], v96 offset:6656
	v_mfma_f32_32x32x16_bf16 v[16:31], v[148:151], v[2:5], v[16:31]
	v_exp_f32_e32 v68, v68
	v_exp_f32_e32 v69, v69
	v_exp_f32_e32 v70, v70
	v_exp_f32_e32 v71, v71
	v_mfma_f32_32x32x16_bf16 v[32:47], v[144:147], v[6:9], v[32:47]
	v_exp_f32_e32 v72, v72
	v_exp_f32_e32 v73, v73
	v_exp_f32_e32 v74, v74
	v_exp_f32_e32 v75, v75
	v_mfma_f32_32x32x16_bf16 v[16:31], v[144:147], v[164:167], v[16:31]
	v_exp_f32_e32 v76, v76
	v_exp_f32_e32 v77, v77
	v_exp_f32_e32 v78, v78
	v_exp_f32_e32 v79, v79
	s_waitcnt vmcnt(2) lgkmcnt(0)
	s_barrier
	s_andn2_b64 vcc, exec, s[16:17]
	s_cbranch_vccnz .LBB0_1319
	s_waitcnt lgkmcnt(0)
	ds_read_b128 v[2:5], v224 offset:49248
	ds_read_b128 v[6:9], v224 offset:49216
	ds_read_b128 v[10:13], v224 offset:49184
	ds_read_b128 v[96:99], v224 offset:49152
	s_waitcnt lgkmcnt(3)
	v_mul_f32_e32 v46, v46, v4
	v_mul_f32_e32 v47, v47, v5
	s_waitcnt lgkmcnt(2)
	v_mul_f32_e32 v42, v42, v8
	v_mul_f32_e32 v43, v43, v9
	s_waitcnt lgkmcnt(1)
	v_mul_f32_e32 v38, v38, v12
	v_mul_f32_e32 v39, v39, v13
	s_waitcnt lgkmcnt(0)
	v_mul_f32_e32 v34, v34, v98
	v_mul_f32_e32 v35, v35, v99
	v_mul_f32_e32 v44, v44, v2
	v_mul_f32_e32 v45, v45, v3
	v_mul_f32_e32 v40, v40, v6
	v_mul_f32_e32 v41, v41, v7
	v_mul_f32_e32 v36, v36, v10
	v_mul_f32_e32 v37, v37, v11
	v_mul_f32_e32 v32, v32, v96
	v_mul_f32_e32 v33, v33, v97
	v_mul_f32_e32 v30, v30, v4
	v_mul_f32_e32 v31, v31, v5
	v_mul_f32_e32 v26, v26, v8
	v_mul_f32_e32 v27, v27, v9
	v_mul_f32_e32 v22, v22, v12
	v_mul_f32_e32 v23, v23, v13
	v_mul_f32_e32 v18, v18, v98
	v_mul_f32_e32 v19, v19, v99
	v_mul_f32_e32 v28, v28, v2
	v_mul_f32_e32 v29, v29, v3
	v_mul_f32_e32 v24, v24, v6
	v_mul_f32_e32 v25, v25, v7
	v_mul_f32_e32 v20, v20, v10
	v_mul_f32_e32 v21, v21, v11
	v_mul_f32_e32 v16, v16, v96
	v_mul_f32_e32 v17, v17, v97
.LBB0_1319:
	s_add_i32 s16, s25, 0x2000
	s_cmpk_lg_i32 s25, 0x4000
	s_cselect_b32 s78, s16, 0
	v_add_u32_e32 v14, s50, v240
	ds_read_b64_tr_b16 v[168:169], v14 offset:24576
	ds_read_b64_tr_b16 v[170:171], v14 offset:25088
	v_add_f32_e32 v2, v80, v81
	v_add_f32_e32 v2, v82, v2
	v_add_f32_e32 v2, v83, v2
	v_add_f32_e32 v2, v84, v2
	v_add_f32_e32 v2, v85, v2
	v_cvt_pk_bf16_f32 v156, v80, v81
	v_cvt_pk_bf16_f32 v157, v82, v83
	s_waitcnt lgkmcnt(9)
	v_mfma_f32_32x32x16_bf16 v[96:111], v[112:115], v[140:143], v[48:63]
	ds_read_b64_tr_b16 v[164:165], v14 offset:28672
	ds_read_b64_tr_b16 v[166:167], v14 offset:29184
	v_add_f32_e32 v2, v86, v2
	v_add_f32_e32 v2, v87, v2
	v_add_f32_e32 v2, v88, v2
	v_add_f32_e32 v2, v89, v2
	v_cvt_pk_bf16_f32 v158, v84, v85
	v_cvt_pk_bf16_f32 v159, v86, v87
	s_waitcnt lgkmcnt(10)
	v_mfma_f32_32x32x16_bf16 v[112:127], v[160:163], v[140:143], v[48:63]
	ds_read_b64_tr_b16 v[10:11], v14 offset:25600
	ds_read_b64_tr_b16 v[12:13], v14 offset:26112
	v_add_f32_e32 v2, v90, v2
	v_add_f32_e32 v2, v91, v2
	v_add_f32_e32 v2, v92, v2
	v_add_f32_e32 v2, v93, v2
	v_cvt_pk_bf16_f32 v152, v88, v89
	v_cvt_pk_bf16_f32 v153, v90, v91
	s_waitcnt lgkmcnt(11)
	v_mfma_f32_32x32x16_bf16 v[96:111], v[192:195], v[136:139], v[96:111]
	ds_read_b64_tr_b16 v[160:161], v14 offset:29696
	ds_read_b64_tr_b16 v[162:163], v14 offset:30208
	v_add_f32_e32 v2, v94, v2
	v_add_f32_e32 v2, v95, v2
	v_add_f32_e32 v2, v64, v2
	v_add_f32_e32 v2, v65, v2
	v_cvt_pk_bf16_f32 v154, v92, v93
	v_cvt_pk_bf16_f32 v155, v94, v95
	s_waitcnt lgkmcnt(12)
	v_mfma_f32_32x32x16_bf16 v[112:127], v[188:191], v[136:139], v[112:127]
	ds_read_b64_tr_b16 v[196:197], v14 offset:26624
	ds_read_b64_tr_b16 v[198:199], v14 offset:27136
	v_add_f32_e32 v2, v66, v2
	v_add_f32_e32 v2, v67, v2
	v_add_f32_e32 v2, v68, v2
	v_add_f32_e32 v6, v69, v2
	v_cvt_pk_bf16_f32 v148, v64, v65
	v_cvt_pk_bf16_f32 v149, v66, v67
	s_waitcnt lgkmcnt(13)
	v_mfma_f32_32x32x16_bf16 v[96:111], v[184:187], v[132:135], v[96:111]
	ds_read_b64_tr_b16 v[2:3], v14 offset:30720
	ds_read_b64_tr_b16 v[4:5], v14 offset:31232
	v_add_f32_e32 v6, v70, v6
	v_add_f32_e32 v6, v71, v6
	v_add_f32_e32 v6, v72, v6
	v_add_f32_e32 v15, v73, v6
	v_cvt_pk_bf16_f32 v150, v68, v69
	v_cvt_pk_bf16_f32 v151, v70, v71
	s_waitcnt lgkmcnt(14)
	v_mfma_f32_32x32x16_bf16 v[112:127], v[180:183], v[132:135], v[112:127]
	ds_read_b64_tr_b16 v[6:7], v14 offset:27648
	ds_read_b64_tr_b16 v[8:9], v14 offset:28160
	v_add_f32_e32 v15, v74, v15
	v_add_f32_e32 v15, v75, v15
	v_add_f32_e32 v15, v76, v15
	v_add_f32_e32 v15, v77, v15
	v_cvt_pk_bf16_f32 v144, v72, v73
	v_cvt_pk_bf16_f32 v145, v74, v75
	s_waitcnt lgkmcnt(14)
	v_mfma_f32_32x32x16_bf16 v[96:111], v[176:179], v[128:131], v[96:111]
	ds_read_b64_tr_b16 v[192:193], v14 offset:31744
	ds_read_b64_tr_b16 v[194:195], v14 offset:32256
	v_add_f32_e32 v14, v78, v15
	v_add_f32_e32 v14, v79, v14
	v_add_f32_e32 v80, 0, v14
	v_cvt_pk_bf16_f32 v146, v76, v77
	v_cvt_pk_bf16_f32 v147, v78, v79
	v_mfma_f32_32x32x16_bf16 v[112:127], v[172:175], v[128:131], v[112:127]
	s_add_i32 s16, s46, -1
	s_add_i32 s17, s47, 0xfffe8000
	s_lshr_b32 s16, s16, 2
	s_and_b32 s22, s17, 0x18000
	v_mad_u64_u32 v[14:15], s[16:17], s16, v239, v[212:213]
	s_lshl_b32 s26, s22, 1
	v_lshl_add_u64 v[14:15], v[14:15], 0, s[26:27]
	s_add_i32 s16, s25, s74
	s_mov_b32 s17, m0
	s_mov_b32 m0, s16
	s_nop 0
	global_load_lds_dwordx4 v[14:15], off
	s_mov_b32 m0, s17
	s_add_i32 s50, s46, -3
	s_add_i32 s17, s47, 0xffff8000
	s_lshr_b32 s16, s50, 2
	s_and_b32 s22, s17, 0x18000
	v_mad_u64_u32 v[14:15], s[16:17], s16, v239, v[214:215]
	s_lshl_b32 s26, s22, 1
	v_lshl_add_u64 v[14:15], v[14:15], 0, s[26:27]
	s_add_i32 s16, s78, s75
	s_mov_b32 s17, m0
	s_mov_b32 m0, s16
	s_nop 0
	global_load_lds_dwordx4 v[14:15], off
	s_mov_b32 m0, s17
	ds_read_b128 v[64:67], v200 offset:256
	ds_read_b128 v[68:71], v200 offset:288
	ds_read_b128 v[72:75], v200 offset:384
	v_add_f32_e32 v241, v0, v80
	s_waitcnt lgkmcnt(2)
	v_add_f32_e32 v82, v98, v66
	v_add_f32_e32 v83, v99, v67
	s_waitcnt lgkmcnt(1)
	v_add_f32_e32 v84, v100, v68
	v_add_f32_e32 v85, v101, v69
	s_waitcnt lgkmcnt(0)
	v_add_f32_e32 v14, v112, v72
	v_add_f32_e32 v15, v113, v73
	v_add_f32_e32 v66, v114, v74
	v_add_f32_e32 v67, v115, v75
	ds_read_b128 v[72:75], v200 offset:416
	v_add_f32_e32 v86, v102, v70
	v_add_f32_e32 v87, v103, v71
	v_add_f32_e32 v64, v96, v64
	v_add_f32_e32 v65, v97, v65
	s_waitcnt lgkmcnt(0)
	v_add_f32_e32 v68, v116, v72
	v_add_f32_e32 v69, v117, v73
	v_add_f32_e32 v70, v118, v74
	v_add_f32_e32 v71, v119, v75
	ds_read_b128 v[72:75], v200 offset:320
	ds_read_b128 v[76:79], v200 offset:448
	v_max_f32_e32 v81, v64, v65
	v_max3_f32 v81, v81, v14, v66
	v_max3_f32 v81, v81, v67, v84
	s_waitcnt lgkmcnt(1)
	v_add_f32_e32 v88, v104, v72
	v_add_f32_e32 v89, v105, v73
	s_waitcnt lgkmcnt(0)
	v_add_f32_e32 v72, v120, v76
	v_add_f32_e32 v73, v121, v77
	v_add_f32_e32 v90, v106, v74
	v_add_f32_e32 v91, v107, v75
	v_add_f32_e32 v74, v122, v78
	v_add_f32_e32 v75, v123, v79
	ds_read_b128 v[76:79], v200 offset:352
	ds_read_b128 v[94:97], v200 offset:480
	v_max3_f32 v81, v81, v85, v68
	v_max3_f32 v81, v81, v69, v88
	v_max3_f32 v81, v81, v89, v72
	s_waitcnt lgkmcnt(1)
	v_add_f32_e32 v92, v108, v76
	v_add_f32_e32 v93, v109, v77
	s_waitcnt lgkmcnt(0)
	v_add_f32_e32 v76, v124, v94
	v_add_f32_e32 v77, v125, v95
	v_add_f32_e32 v94, v110, v78
	v_add_f32_e32 v95, v111, v79
	v_add_f32_e32 v78, v126, v96
	v_add_f32_e32 v79, v127, v97
	v_max3_f32 v96, v82, v83, v15
	v_max3_f32 v96, v96, v86, v87
	v_max3_f32 v96, v96, v70, v71
	v_max3_f32 v96, v96, v90, v91
	v_max3_f32 v96, v96, v74, v75
	v_max3_f32 v81, v81, v73, v92
	v_max3_f32 v96, v96, v94, v95
	v_max3_f32 v81, v81, v93, v76
	v_max3_f32 v96, v96, v78, v79
	v_max3_f32 v0, v81, v77, v96
	v_mov_b32_e32 v80, v0
	s_nop 1
	v_permlane32_swap_b32_e32 v0, v80
	v_max_f32_e32 v80, v80, v80
	v_max_f32_e32 v0, v0, v0
	v_max_f32_e32 v0, v0, v80
	v_cmp_lt_f32_e32 vcc, s36, v0
	s_cmp_lg_u64 vcc, 0
	s_cselect_b64 s[16:17], -1, 0
	s_cbranch_vccnz .LBB0_1327
.LBB0_1320:
	v_mfma_f32_32x32x16_bf16 v[32:47], v[156:159], v[168:171], v[32:47]
	v_exp_f32_e32 v80, v64
	v_exp_f32_e32 v81, v65
	v_exp_f32_e32 v82, v82
	v_exp_f32_e32 v83, v83
	v_mfma_f32_32x32x16_bf16 v[16:31], v[156:159], v[164:167], v[16:31]
	v_exp_f32_e32 v84, v84
	v_exp_f32_e32 v85, v85
	v_exp_f32_e32 v86, v86
	v_exp_f32_e32 v87, v87
	v_add_u32_e32 v0, s78, v228
	ds_read_b128 v[188:191], v0
	ds_read_b128 v[184:187], v0 offset:512
	v_mfma_f32_32x32x16_bf16 v[32:47], v[152:155], v[10:13], v[32:47]
	v_exp_f32_e32 v88, v88
	v_exp_f32_e32 v89, v89
	v_exp_f32_e32 v90, v90
	v_exp_f32_e32 v91, v91
	ds_read_b128 v[180:183], v0 offset:2048
	ds_read_b128 v[176:179], v0 offset:2560
	v_mfma_f32_32x32x16_bf16 v[16:31], v[152:155], v[160:163], v[16:31]
	v_exp_f32_e32 v92, v92
	v_exp_f32_e32 v93, v93
	v_exp_f32_e32 v94, v94
	v_exp_f32_e32 v95, v95
	ds_read_b128 v[172:175], v0 offset:4096
	ds_read_b128 v[168:171], v0 offset:4608
	v_mfma_f32_32x32x16_bf16 v[32:47], v[148:151], v[196:199], v[32:47]
	v_exp_f32_e32 v64, v14
	v_exp_f32_e32 v65, v15
	v_exp_f32_e32 v66, v66
	v_exp_f32_e32 v67, v67
	ds_read_b128 v[164:167], v0 offset:6144
	ds_read_b128 v[160:163], v0 offset:6656
	v_mfma_f32_32x32x16_bf16 v[16:31], v[148:151], v[2:5], v[16:31]
	v_exp_f32_e32 v68, v68
	v_exp_f32_e32 v69, v69
	v_exp_f32_e32 v70, v70
	v_exp_f32_e32 v71, v71
	v_mfma_f32_32x32x16_bf16 v[32:47], v[144:147], v[6:9], v[32:47]
	v_exp_f32_e32 v72, v72
	v_exp_f32_e32 v73, v73
	v_exp_f32_e32 v74, v74
	v_exp_f32_e32 v75, v75
	v_mfma_f32_32x32x16_bf16 v[16:31], v[144:147], v[192:195], v[16:31]
	v_exp_f32_e32 v76, v76
	v_exp_f32_e32 v77, v77
	v_exp_f32_e32 v78, v78
	v_exp_f32_e32 v79, v79
	s_waitcnt vmcnt(2) lgkmcnt(0)
	s_barrier
	s_andn2_b64 vcc, exec, s[16:17]
	s_cbranch_vccnz .LBB0_1322
	s_waitcnt lgkmcnt(0)
	ds_read_b128 v[2:5], v224 offset:49248
	ds_read_b128 v[6:9], v224 offset:49216
	ds_read_b128 v[10:13], v224 offset:49184
	ds_read_b128 v[96:99], v224 offset:49152
	s_waitcnt lgkmcnt(3)
	v_mul_f32_e32 v46, v46, v4
	v_mul_f32_e32 v47, v47, v5
	s_waitcnt lgkmcnt(2)
	v_mul_f32_e32 v42, v42, v8
	v_mul_f32_e32 v43, v43, v9
	s_waitcnt lgkmcnt(1)
	v_mul_f32_e32 v38, v38, v12
	v_mul_f32_e32 v39, v39, v13
	s_waitcnt lgkmcnt(0)
	v_mul_f32_e32 v34, v34, v98
	v_mul_f32_e32 v35, v35, v99
	v_mul_f32_e32 v44, v44, v2
	v_mul_f32_e32 v45, v45, v3
	v_mul_f32_e32 v40, v40, v6
	v_mul_f32_e32 v41, v41, v7
	v_mul_f32_e32 v36, v36, v10
	v_mul_f32_e32 v37, v37, v11
	v_mul_f32_e32 v32, v32, v96
	v_mul_f32_e32 v33, v33, v97
	v_mul_f32_e32 v30, v30, v4
	v_mul_f32_e32 v31, v31, v5
	v_mul_f32_e32 v26, v26, v8
	v_mul_f32_e32 v27, v27, v9
	v_mul_f32_e32 v22, v22, v12
	v_mul_f32_e32 v23, v23, v13
	v_mul_f32_e32 v18, v18, v98
	v_mul_f32_e32 v19, v19, v99
	v_mul_f32_e32 v28, v28, v2
	v_mul_f32_e32 v29, v29, v3
	v_mul_f32_e32 v24, v24, v6
	v_mul_f32_e32 v25, v25, v7
	v_mul_f32_e32 v20, v20, v10
	v_mul_f32_e32 v21, v21, v11
	v_mul_f32_e32 v16, v16, v96
	v_mul_f32_e32 v17, v17, v97

.LBB0_1335:
	s_add_i32 s4, s58, -1
	s_add_i32 s5, s79, 0x8000
	s_lshr_b32 s4, s4, 2
	s_and_b32 s24, s5, 0x18000
	v_mad_u64_u32 v[64:65], s[4:5], s4, v239, v[214:215]
	s_lshl_b32 s26, s24, 1
	v_lshl_add_u64 v[64:65], v[64:65], 0, s[26:27]
	s_add_i32 s4, s64, s75
	s_mov_b32 s5, m0
	s_mov_b32 m0, s4
	s_nop 0
	global_load_lds_dwordx4 v[64:65], off
	s_mov_b32 m0, s5
	ds_read_b128 v[64:67], v14
	ds_read_b128 v[68:71], v14 offset:32
	ds_read_b128 v[72:75], v14 offset:64
	ds_read_b128 v[76:79], v14 offset:96
	ds_read_b128 v[160:163], v14 offset:128
	ds_read_b128 v[164:167], v14 offset:160
	ds_read_b128 v[168:171], v14 offset:192
	ds_read_b128 v[172:175], v14 offset:224
	s_add_i32 s59, s65, s58
	s_add_i32 s4, s59, -2
	s_waitcnt lgkmcnt(4)
	v_add_f32_e32 v94, v126, v78
	v_add_f32_e32 v95, v127, v79
	v_add_f32_e32 v90, v122, v74
	v_add_f32_e32 v91, v123, v75
	v_add_f32_e32 v86, v118, v70
	v_add_f32_e32 v87, v119, v71
	v_add_f32_e32 v82, v114, v66
	v_add_f32_e32 v83, v115, v67
	v_add_f32_e32 v92, v124, v76
	v_add_f32_e32 v93, v125, v77
	v_add_f32_e32 v88, v120, v72
	v_add_f32_e32 v89, v121, v73
	v_add_f32_e32 v84, v116, v68
	v_add_f32_e32 v85, v117, v69
	v_add_f32_e32 v80, v112, v64
	v_add_f32_e32 v81, v113, v65
	s_waitcnt lgkmcnt(0)
	v_add_f32_e32 v78, v110, v174
	v_add_f32_e32 v79, v111, v175
	v_add_f32_e32 v74, v106, v170
	v_add_f32_e32 v75, v107, v171
	v_add_f32_e32 v70, v102, v166
	v_add_f32_e32 v71, v103, v167
	v_add_f32_e32 v66, v98, v162
	v_add_f32_e32 v67, v99, v163
	v_add_f32_e32 v76, v108, v172
	v_add_f32_e32 v77, v109, v173
	v_add_f32_e32 v72, v104, v168
	v_add_f32_e32 v73, v105, v169
	v_add_f32_e32 v68, v100, v164
	v_add_f32_e32 v69, v101, v165
	s_cmp_lt_i32 s4, 0
	v_add_f32_e32 v64, v96, v160
	v_add_f32_e32 v65, v97, v161
	s_cbranch_scc1 .LBB0_1337
	v_add_u32_e32 v97, 0xffffffa5, v0
	v_add_u32_e32 v96, 0xffffff85, v0
	v_cmp_le_i32_e32 vcc, v97, v227
	s_nop 1
	v_cndmask_b32_e32 v64, v238, v64, vcc
	v_cmp_lt_i32_e32 vcc, v96, v227
	s_nop 1
	v_cndmask_b32_e32 v81, v238, v81, vcc
	v_cmp_le_i32_e32 vcc, v96, v227
	v_add_u32_e32 v96, 0xffffffa6, v0
	s_nop 0
	v_cndmask_b32_e32 v80, v238, v80, vcc
	v_cmp_le_i32_e32 vcc, v96, v227
	v_add_u32_e32 v96, 0xffffff87, v0
	s_nop 0
	v_cndmask_b32_e32 v65, v238, v65, vcc
	v_cmp_le_i32_e32 vcc, v96, v227
	v_add_u32_e32 v96, 0xffffffa7, v0
	s_nop 0
	v_cndmask_b32_e32 v82, v238, v82, vcc
	v_cmp_le_i32_e32 vcc, v96, v227
	v_add_u32_e32 v96, 0xffffff88, v0
	s_nop 0
	v_cndmask_b32_e32 v66, v238, v66, vcc
	v_cmp_le_i32_e32 vcc, v96, v227
	v_add_u32_e32 v96, 0xffffffa8, v0
	s_nop 0
	v_cndmask_b32_e32 v83, v238, v83, vcc
	v_cmp_le_i32_e32 vcc, v96, v227
	v_add_u32_e32 v96, 0xffffff8d, v0
	s_nop 0
	v_cndmask_b32_e32 v67, v238, v67, vcc
	v_cmp_le_i32_e32 vcc, v96, v227
	v_add_u32_e32 v96, 0xffffffad, v0
	s_nop 0
	v_cndmask_b32_e32 v84, v238, v84, vcc
	v_cmp_le_i32_e32 vcc, v96, v227
	v_add_u32_e32 v96, 0xffffff8e, v0
	s_nop 0
	v_cndmask_b32_e32 v68, v238, v68, vcc
	v_cmp_le_i32_e32 vcc, v96, v227
	v_add_u32_e32 v96, 0xffffffae, v0
	s_nop 0
	v_cndmask_b32_e32 v85, v238, v85, vcc
	v_cmp_le_i32_e32 vcc, v96, v227
	v_add_u32_e32 v96, 0xffffff8f, v0
	s_nop 0
	v_cndmask_b32_e32 v69, v238, v69, vcc
	v_cmp_le_i32_e32 vcc, v96, v227
	v_add_u32_e32 v96, 0xffffffaf, v0
	s_nop 0
	v_cndmask_b32_e32 v86, v238, v86, vcc
	v_cmp_le_i32_e32 vcc, v96, v227
	v_add_u32_e32 v96, 0xffffff90, v0
	s_nop 0
	v_cndmask_b32_e32 v70, v238, v70, vcc
	v_cmp_le_i32_e32 vcc, v96, v227
	v_add_u32_e32 v96, 0xffffffb0, v0
	s_nop 0
	v_cndmask_b32_e32 v87, v238, v87, vcc
	v_cmp_le_i32_e32 vcc, v96, v227
	v_add_u32_e32 v96, 0xffffff95, v0
	s_nop 0
	v_cndmask_b32_e32 v71, v238, v71, vcc
	v_cmp_le_i32_e32 vcc, v96, v227
	v_add_u32_e32 v96, 0xffffffb5, v0
	s_nop 0
	v_cndmask_b32_e32 v88, v238, v88, vcc
	v_cmp_le_i32_e32 vcc, v96, v227
	v_add_u32_e32 v96, 0xffffff96, v0
	s_nop 0
	v_cndmask_b32_e32 v72, v238, v72, vcc
	v_cmp_le_i32_e32 vcc, v96, v227
	v_add_u32_e32 v96, 0xffffffb6, v0
	s_nop 0
	v_cndmask_b32_e32 v89, v238, v89, vcc
	v_cmp_le_i32_e32 vcc, v96, v227
	v_add_u32_e32 v96, 0xffffff97, v0
	s_nop 0
	v_cndmask_b32_e32 v73, v238, v73, vcc
	v_cmp_le_i32_e32 vcc, v96, v227
	v_add_u32_e32 v96, 0xffffffb7, v0
	s_nop 0
	v_cndmask_b32_e32 v90, v238, v90, vcc
	v_cmp_le_i32_e32 vcc, v96, v227
	v_add_u32_e32 v96, 0xffffff98, v0
	s_nop 0
	v_cndmask_b32_e32 v74, v238, v74, vcc
	v_cmp_le_i32_e32 vcc, v96, v227
	v_add_u32_e32 v96, 0xffffffb8, v0
	s_nop 0
	v_cndmask_b32_e32 v91, v238, v91, vcc
	v_cmp_le_i32_e32 vcc, v96, v227
	v_add_u32_e32 v96, 0xffffff9d, v0
	s_nop 0
	v_cndmask_b32_e32 v75, v238, v75, vcc
	v_cmp_le_i32_e32 vcc, v96, v227
	v_add_u32_e32 v96, 0xffffffbd, v0
	s_nop 0
	v_cndmask_b32_e32 v92, v238, v92, vcc
	v_cmp_le_i32_e32 vcc, v96, v227
	v_add_u32_e32 v96, 0xffffff9e, v0
	s_nop 0
	v_cndmask_b32_e32 v76, v238, v76, vcc
	v_cmp_le_i32_e32 vcc, v96, v227
	v_add_u32_e32 v96, 0xffffffbe, v0
	s_nop 0
	v_cndmask_b32_e32 v93, v238, v93, vcc
	v_cmp_le_i32_e32 vcc, v96, v227
	v_add_u32_e32 v96, 0xffffff9f, v0
	s_nop 0
	v_cndmask_b32_e32 v77, v238, v77, vcc
	v_cmp_le_i32_e32 vcc, v96, v227
	v_add_u32_e32 v96, 0xffffffbf, v0
	s_nop 0
	v_cndmask_b32_e32 v94, v238, v94, vcc
	v_cmp_le_i32_e32 vcc, v96, v227
	v_add_u32_e32 v96, 0xffffffa0, v0
	s_nop 0
	v_cndmask_b32_e32 v78, v238, v78, vcc
	v_cmp_le_i32_e32 vcc, v96, v227
	v_subrev_u32_e32 v96, 64, v0
	s_nop 0
	v_cndmask_b32_e32 v95, v238, v95, vcc
	v_cmp_le_i32_e32 vcc, v96, v227
	s_nop 1
	v_cndmask_b32_e32 v79, v238, v79, vcc

.LBB0_1345:
	s_waitcnt lgkmcnt(0)
	ds_read_b128 v[2:5], v224 offset:49248
	ds_read_b128 v[6:9], v224 offset:49216
	ds_read_b128 v[10:13], v224 offset:49184
	ds_read_b128 v[96:99], v224 offset:49152
	s_waitcnt lgkmcnt(3)
	v_mul_f32_e32 v46, v46, v4
	v_mul_f32_e32 v47, v47, v5
	s_waitcnt lgkmcnt(2)
	v_mul_f32_e32 v42, v42, v8
	v_mul_f32_e32 v43, v43, v9
	s_waitcnt lgkmcnt(1)
	v_mul_f32_e32 v38, v38, v12
	v_mul_f32_e32 v39, v39, v13
	s_waitcnt lgkmcnt(0)
	v_mul_f32_e32 v34, v34, v98
	v_mul_f32_e32 v35, v35, v99
	v_mul_f32_e32 v44, v44, v2
	v_mul_f32_e32 v45, v45, v3
	v_mul_f32_e32 v40, v40, v6
	v_mul_f32_e32 v41, v41, v7
	v_mul_f32_e32 v36, v36, v10
	v_mul_f32_e32 v37, v37, v11
	v_mul_f32_e32 v32, v32, v96
	v_mul_f32_e32 v33, v33, v97
	v_mul_f32_e32 v30, v30, v4
	v_mul_f32_e32 v31, v31, v5
	v_mul_f32_e32 v26, v26, v8
	v_mul_f32_e32 v27, v27, v9
	v_mul_f32_e32 v22, v22, v12
	v_mul_f32_e32 v23, v23, v13
	v_mul_f32_e32 v18, v18, v98
	v_mul_f32_e32 v19, v19, v99
	v_mul_f32_e32 v28, v28, v2
	v_mul_f32_e32 v29, v29, v3
	v_mul_f32_e32 v24, v24, v6
	v_mul_f32_e32 v25, v25, v7
	v_mul_f32_e32 v20, v20, v10
	v_mul_f32_e32 v21, v21, v11
	v_mul_f32_e32 v16, v16, v96
	v_mul_f32_e32 v17, v17, v97

.LBB0_1350:
	ds_read_b128 v[64:67], v14 offset:256
	ds_read_b128 v[68:71], v14 offset:288
	ds_read_b128 v[72:75], v14 offset:320
	ds_read_b128 v[76:79], v14 offset:352
	ds_read_b128 v[242:245], v14 offset:384
	ds_read_b128 v[246:249], v14 offset:416
	ds_read_b128 v[250:253], v14 offset:448
	ds_read_b128 v[232:235], v14 offset:480
	s_add_i32 s59, s59, -1
	s_waitcnt lgkmcnt(4)
	v_add_f32_e32 v94, v126, v78
	v_add_f32_e32 v95, v127, v79
	v_add_f32_e32 v90, v122, v74
	v_add_f32_e32 v91, v123, v75
	v_add_f32_e32 v86, v118, v70
	v_add_f32_e32 v87, v119, v71
	v_add_f32_e32 v82, v114, v66
	v_add_f32_e32 v83, v115, v67
	v_add_f32_e32 v92, v124, v76
	v_add_f32_e32 v93, v125, v77
	v_add_f32_e32 v88, v120, v72
	v_add_f32_e32 v89, v121, v73
	v_add_f32_e32 v84, v116, v68
	v_add_f32_e32 v85, v117, v69
	v_add_f32_e32 v80, v112, v64
	v_add_f32_e32 v81, v113, v65
	s_waitcnt lgkmcnt(0)
	v_add_f32_e32 v78, v110, v234
	v_add_f32_e32 v79, v111, v235
	v_add_f32_e32 v74, v106, v252
	v_add_f32_e32 v75, v107, v253
	v_add_f32_e32 v70, v102, v248
	v_add_f32_e32 v71, v103, v249
	v_add_f32_e32 v66, v98, v244
	v_add_f32_e32 v67, v99, v245
	v_add_f32_e32 v76, v108, v232
	v_add_f32_e32 v77, v109, v233
	v_add_f32_e32 v72, v104, v250
	v_add_f32_e32 v73, v105, v251
	v_add_f32_e32 v68, v100, v246
	v_add_f32_e32 v69, v101, v247
	s_cmp_lt_i32 s59, 0
	v_add_f32_e32 v64, v96, v242
	v_add_f32_e32 v65, v97, v243
	s_cbranch_scc1 .LBB0_1352
	v_subrev_u32_e32 v97, 27, v0
	v_subrev_u32_e32 v96, 59, v0
	v_cmp_le_i32_e32 vcc, v97, v227
	s_nop 1
	v_cndmask_b32_e32 v64, v238, v64, vcc
	v_cmp_lt_i32_e32 vcc, v96, v227
	s_nop 1
	v_cndmask_b32_e32 v81, v238, v81, vcc
	v_cmp_le_i32_e32 vcc, v96, v227
	v_subrev_u32_e32 v96, 26, v0
	s_nop 0
	v_cndmask_b32_e32 v80, v238, v80, vcc
	v_cmp_le_i32_e32 vcc, v96, v227
	v_subrev_u32_e32 v96, 57, v0
	s_nop 0
	v_cndmask_b32_e32 v65, v238, v65, vcc
	v_cmp_le_i32_e32 vcc, v96, v227
	v_subrev_u32_e32 v96, 25, v0
	s_nop 0
	v_cndmask_b32_e32 v82, v238, v82, vcc
	v_cmp_le_i32_e32 vcc, v96, v227
	v_subrev_u32_e32 v96, 56, v0
	s_nop 0
	v_cndmask_b32_e32 v66, v238, v66, vcc
	v_cmp_le_i32_e32 vcc, v96, v227
	v_subrev_u32_e32 v96, 24, v0
	s_nop 0
	v_cndmask_b32_e32 v83, v238, v83, vcc
	v_cmp_le_i32_e32 vcc, v96, v227
	v_subrev_u32_e32 v96, 51, v0
	s_nop 0
	v_cndmask_b32_e32 v67, v238, v67, vcc
	v_cmp_le_i32_e32 vcc, v96, v227
	v_subrev_u32_e32 v96, 19, v0
	s_nop 0
	v_cndmask_b32_e32 v84, v238, v84, vcc
	v_cmp_le_i32_e32 vcc, v96, v227
	v_subrev_u32_e32 v96, 50, v0
	s_nop 0
	v_cndmask_b32_e32 v68, v238, v68, vcc
	v_cmp_le_i32_e32 vcc, v96, v227
	v_subrev_u32_e32 v96, 18, v0
	s_nop 0
	v_cndmask_b32_e32 v85, v238, v85, vcc
	v_cmp_le_i32_e32 vcc, v96, v227
	v_subrev_u32_e32 v96, 49, v0
	s_nop 0
	v_cndmask_b32_e32 v69, v238, v69, vcc
	v_cmp_le_i32_e32 vcc, v96, v227
	v_subrev_u32_e32 v96, 17, v0
	s_nop 0
	v_cndmask_b32_e32 v86, v238, v86, vcc
	v_cmp_le_i32_e32 vcc, v96, v227
	v_subrev_u32_e32 v96, 48, v0
	s_nop 0
	v_cndmask_b32_e32 v70, v238, v70, vcc
	v_cmp_le_i32_e32 vcc, v96, v227
	v_add_u32_e32 v96, -16, v0
	s_nop 0
	v_cndmask_b32_e32 v87, v238, v87, vcc
	v_cmp_le_i32_e32 vcc, v96, v227
	v_subrev_u32_e32 v96, 43, v0
	s_nop 0
	v_cndmask_b32_e32 v71, v238, v71, vcc
	v_cmp_le_i32_e32 vcc, v96, v227
	v_add_u32_e32 v96, -11, v0
	s_nop 0
	v_cndmask_b32_e32 v88, v238, v88, vcc
	v_cmp_le_i32_e32 vcc, v96, v227
	v_subrev_u32_e32 v96, 42, v0
	s_nop 0
	v_cndmask_b32_e32 v72, v238, v72, vcc
	v_cmp_le_i32_e32 vcc, v96, v227
	v_add_u32_e32 v96, -10, v0
	s_nop 0
	v_cndmask_b32_e32 v89, v238, v89, vcc
	v_cmp_le_i32_e32 vcc, v96, v227
	v_subrev_u32_e32 v96, 41, v0
	s_nop 0
	v_cndmask_b32_e32 v73, v238, v73, vcc
	v_cmp_le_i32_e32 vcc, v96, v227
	v_add_u32_e32 v96, -9, v0
	s_nop 0
	v_cndmask_b32_e32 v90, v238, v90, vcc
	v_cmp_le_i32_e32 vcc, v96, v227
	v_subrev_u32_e32 v96, 40, v0
	s_nop 0
	v_cndmask_b32_e32 v74, v238, v74, vcc
	v_cmp_le_i32_e32 vcc, v96, v227
	v_add_u32_e32 v96, -8, v0
	s_nop 0
	v_cndmask_b32_e32 v91, v238, v91, vcc
	v_cmp_le_i32_e32 vcc, v96, v227
	v_subrev_u32_e32 v96, 35, v0
	s_nop 0
	v_cndmask_b32_e32 v75, v238, v75, vcc
	v_cmp_le_i32_e32 vcc, v96, v227
	v_add_u32_e32 v96, -3, v0
	s_nop 0
	v_cndmask_b32_e32 v92, v238, v92, vcc
	v_cmp_le_i32_e32 vcc, v96, v227
	v_subrev_u32_e32 v96, 34, v0
	s_nop 0
	v_cndmask_b32_e32 v76, v238, v76, vcc
	v_cmp_le_i32_e32 vcc, v96, v227
	v_add_u32_e32 v96, -2, v0
	s_nop 0
	v_cndmask_b32_e32 v93, v238, v93, vcc
	v_cmp_le_i32_e32 vcc, v96, v227
	v_subrev_u32_e32 v96, 33, v0
	s_nop 0
	v_cndmask_b32_e32 v77, v238, v77, vcc
	v_cmp_le_i32_e32 vcc, v96, v227
	v_add_u32_e32 v96, -1, v0
	s_nop 0
	v_cndmask_b32_e32 v94, v238, v94, vcc
	v_cmp_le_i32_e32 vcc, v96, v227
	v_subrev_u32_e32 v96, 32, v0
	s_nop 0
	v_cndmask_b32_e32 v78, v238, v78, vcc
	v_cmp_le_i32_e32 vcc, v96, v227
	s_nop 1
	v_cndmask_b32_e32 v95, v238, v95, vcc
	v_cmp_le_i32_e32 vcc, v0, v227
	s_nop 1
	v_cndmask_b32_e32 v79, v238, v79, vcc

.LBB0_1382:
	v_add_u32_e32 v0, s64, v240
	ds_read_b64_tr_b16 v[6:7], v0 offset:24576
	ds_read_b64_tr_b16 v[8:9], v0 offset:25088
	v_add_f32_e32 v2, v80, v81
	v_add_f32_e32 v2, v82, v2
	v_add_f32_e32 v2, v83, v2
	v_add_f32_e32 v2, v84, v2
	v_add_f32_e32 v10, v85, v2
	v_cvt_pk_bf16_f32 v156, v80, v81
	v_cvt_pk_bf16_f32 v157, v82, v83
	s_waitcnt lgkmcnt(3)
	v_mfma_f32_32x32x16_bf16 v[96:111], v[188:191], v[140:143], v[48:63]
	ds_read_b64_tr_b16 v[2:3], v0 offset:28672
	ds_read_b64_tr_b16 v[4:5], v0 offset:29184
	s_waitcnt lgkmcnt(4)
	v_mfma_f32_32x32x16_bf16 v[48:63], v[184:187], v[140:143], v[48:63]
	v_add_f32_e32 v10, v86, v10
	v_add_f32_e32 v10, v87, v10
	v_add_f32_e32 v10, v88, v10
	v_add_f32_e32 v14, v89, v10
	v_cvt_pk_bf16_f32 v158, v84, v85
	v_cvt_pk_bf16_f32 v159, v86, v87
	ds_read_b64_tr_b16 v[10:11], v0 offset:25600
	ds_read_b64_tr_b16 v[12:13], v0 offset:26112
	v_add_f32_e32 v14, v90, v14
	v_add_f32_e32 v14, v91, v14
	v_add_f32_e32 v14, v92, v14
	v_add_f32_e32 v14, v93, v14
	v_cvt_pk_bf16_f32 v152, v88, v89
	v_cvt_pk_bf16_f32 v153, v90, v91
	v_mfma_f32_32x32x16_bf16 v[96:111], v[180:183], v[136:139], v[96:111]
	ds_read_b64_tr_b16 v[112:113], v0 offset:29696
	ds_read_b64_tr_b16 v[114:115], v0 offset:30208
	v_mfma_f32_32x32x16_bf16 v[48:63], v[176:179], v[136:139], v[48:63]
	v_add_f32_e32 v14, v94, v14
	v_add_f32_e32 v14, v95, v14
	v_add_f32_e32 v14, v64, v14
	v_add_f32_e32 v14, v65, v14
	v_cvt_pk_bf16_f32 v154, v92, v93
	v_cvt_pk_bf16_f32 v155, v94, v95
	ds_read_b64_tr_b16 v[116:117], v0 offset:26624
	ds_read_b64_tr_b16 v[118:119], v0 offset:27136
	v_add_f32_e32 v14, v66, v14
	v_add_f32_e32 v14, v67, v14
	v_add_f32_e32 v14, v68, v14
	v_add_f32_e32 v14, v69, v14
	v_cvt_pk_bf16_f32 v148, v64, v65
	v_cvt_pk_bf16_f32 v149, v66, v67
	v_mfma_f32_32x32x16_bf16 v[96:111], v[172:175], v[132:135], v[96:111]
	ds_read_b64_tr_b16 v[120:121], v0 offset:30720
	ds_read_b64_tr_b16 v[122:123], v0 offset:31232
	v_mfma_f32_32x32x16_bf16 v[48:63], v[168:171], v[132:135], v[48:63]
	v_add_f32_e32 v14, v70, v14
	v_add_f32_e32 v14, v71, v14
	v_add_f32_e32 v14, v72, v14
	v_add_f32_e32 v14, v73, v14
	v_cvt_pk_bf16_f32 v150, v68, v69
	v_cvt_pk_bf16_f32 v151, v70, v71
	ds_read_b64_tr_b16 v[124:125], v0 offset:27648
	ds_read_b64_tr_b16 v[126:127], v0 offset:28160
	v_add_f32_e32 v14, v74, v14
	v_add_f32_e32 v14, v75, v14
	v_add_f32_e32 v14, v76, v14
	v_add_f32_e32 v14, v77, v14
	v_cvt_pk_bf16_f32 v144, v72, v73
	v_cvt_pk_bf16_f32 v145, v74, v75
	v_mfma_f32_32x32x16_bf16 v[96:111], v[164:167], v[128:131], v[96:111]
	ds_read_b64_tr_b16 v[132:133], v0 offset:31744
	ds_read_b64_tr_b16 v[134:135], v0 offset:32256
	v_mfma_f32_32x32x16_bf16 v[48:63], v[160:163], v[128:131], v[48:63]
	v_add_f32_e32 v0, v78, v14
	v_add_f32_e32 v0, v79, v0
	v_add_f32_e32 v0, 0, v0
	v_cvt_pk_bf16_f32 v146, v76, v77
	v_cvt_pk_bf16_f32 v147, v78, v79
	v_lshl_add_u32 v14, s76, 2, v225
	v_add_u32_e32 v15, 0xffffff00, v14
	v_add_u32_e32 v68, 0xffffff80, v14
	ds_read_b128 v[64:67], v15
	ds_read_b128 v[68:71], v68
	v_add_u32_e32 v15, 0xffffff20, v14
	v_add_u32_e32 v76, 0xffffffa0, v14
	ds_read_b128 v[72:75], v15
	ds_read_b128 v[76:79], v76
	v_add_u32_e32 v15, 0xffffff40, v14
	v_subrev_u32_e32 v84, 64, v14
	ds_read_b128 v[80:83], v15
	ds_read_b128 v[84:87], v84
	v_add_u32_e32 v15, 0xffffff60, v14
	v_subrev_u32_e32 v14, 32, v14
	ds_read_b128 v[88:91], v15
	ds_read_b128 v[92:95], v14
	s_waitcnt lgkmcnt(7)
	v_add_f32_e32 v14, v98, v66
	v_add_f32_e32 v15, v99, v67
	v_or_b32_e32 v67, 0xe0, v221
	s_waitcnt lgkmcnt(6)
	v_add_f32_e32 v48, v48, v68
	v_add_f32_e32 v49, v49, v69
	v_or_b32_e32 v66, 0xc0, v221
	v_cmp_le_i32_e32 vcc, v67, v227
	v_add_f32_e32 v64, v96, v64
	v_add_f32_e32 v65, v97, v65
	v_add_f32_e32 v50, v50, v70
	v_add_f32_e32 v51, v51, v71
	v_cndmask_b32_e32 v48, v238, v48, vcc
	v_cmp_lt_i32_e32 vcc, v66, v227
	s_waitcnt lgkmcnt(5)
	v_add_f32_e32 v72, v100, v72
	v_add_f32_e32 v73, v101, v73
	s_waitcnt lgkmcnt(4)
	v_add_f32_e32 v52, v52, v76
	v_add_f32_e32 v53, v53, v77
	v_cndmask_b32_e32 v65, v238, v65, vcc
	v_cmp_le_i32_e32 vcc, v66, v227
	v_or_b32_e32 v66, 0xe1, v221
	v_add_f32_e32 v74, v102, v74
	v_add_f32_e32 v75, v103, v75
	v_cndmask_b32_e32 v64, v238, v64, vcc
	v_cmp_le_i32_e32 vcc, v66, v227
	v_or_b32_e32 v66, 0xc2, v221
	v_add_f32_e32 v54, v54, v78
	v_add_f32_e32 v55, v55, v79
	v_cndmask_b32_e32 v49, v238, v49, vcc
	v_cmp_le_i32_e32 vcc, v66, v227
	s_waitcnt lgkmcnt(3)
	v_add_f32_e32 v80, v104, v80
	v_add_f32_e32 v81, v105, v81
	s_waitcnt lgkmcnt(2)
	v_add_f32_e32 v56, v56, v84
	v_add_f32_e32 v57, v57, v85
	v_cndmask_b32_e32 v66, v238, v14, vcc
	v_or_b32_e32 v14, 0xe2, v221
	v_cmp_le_i32_e32 vcc, v14, v227
	v_or_b32_e32 v14, 0xc3, v221
	v_add_f32_e32 v82, v106, v82
	v_add_f32_e32 v83, v107, v83
	v_cndmask_b32_e32 v50, v238, v50, vcc
	v_cmp_le_i32_e32 vcc, v14, v227
	v_or_b32_e32 v14, 0xe3, v221
	v_add_f32_e32 v58, v58, v86
	v_add_f32_e32 v59, v59, v87
	v_cndmask_b32_e32 v67, v238, v15, vcc
	v_cmp_le_i32_e32 vcc, v14, v227
	v_or_b32_e32 v14, 0xc8, v221
	s_waitcnt lgkmcnt(1)
	v_add_f32_e32 v88, v108, v88
	v_add_f32_e32 v89, v109, v89
	v_cndmask_b32_e32 v51, v238, v51, vcc
	v_cmp_le_i32_e32 vcc, v14, v227
	v_or_b32_e32 v14, 0xe8, v221
	s_waitcnt lgkmcnt(0)
	v_add_f32_e32 v60, v60, v92
	v_add_f32_e32 v61, v61, v93
	v_cndmask_b32_e32 v68, v238, v72, vcc
	v_cmp_le_i32_e32 vcc, v14, v227
	v_or_b32_e32 v14, 0xc9, v221
	v_add_f32_e32 v90, v110, v90
	v_add_f32_e32 v91, v111, v91
	v_cndmask_b32_e32 v52, v238, v52, vcc
	v_cmp_le_i32_e32 vcc, v14, v227
	v_or_b32_e32 v14, 0xe9, v221
	v_add_f32_e32 v62, v62, v94
	v_add_f32_e32 v63, v63, v95
	v_cndmask_b32_e32 v69, v238, v73, vcc
	v_cmp_le_i32_e32 vcc, v14, v227
	v_or_b32_e32 v14, 0xca, v221
	v_max3_f32 v15, v66, v67, v49
	v_cndmask_b32_e32 v53, v238, v53, vcc
	v_cmp_le_i32_e32 vcc, v14, v227
	v_or_b32_e32 v14, 0xea, v221
	v_add_f32_e32 v0, v241, v0
	v_cndmask_b32_e32 v70, v238, v74, vcc
	v_cmp_le_i32_e32 vcc, v14, v227
	v_or_b32_e32 v14, 0xcb, v221
	s_nop 0
	v_cndmask_b32_e32 v54, v238, v54, vcc
	v_cmp_le_i32_e32 vcc, v14, v227
	v_or_b32_e32 v14, 0xeb, v221
	s_nop 0
	v_cndmask_b32_e32 v71, v238, v75, vcc
	v_cmp_le_i32_e32 vcc, v14, v227
	v_or_b32_e32 v14, 0xd0, v221
	v_max3_f32 v15, v15, v70, v71
	v_cndmask_b32_e32 v55, v238, v55, vcc
	v_cmp_le_i32_e32 vcc, v14, v227
	v_or_b32_e32 v14, 0xf0, v221
	v_max3_f32 v15, v15, v54, v55
	v_cndmask_b32_e32 v72, v238, v80, vcc
	v_cmp_le_i32_e32 vcc, v14, v227
	v_or_b32_e32 v14, 0xd1, v221
	s_nop 0
	v_cndmask_b32_e32 v56, v238, v56, vcc
	v_cmp_le_i32_e32 vcc, v14, v227
	v_or_b32_e32 v14, 0xf1, v221
	s_nop 0
	v_cndmask_b32_e32 v73, v238, v81, vcc
	v_cmp_le_i32_e32 vcc, v14, v227
	v_or_b32_e32 v14, 0xd2, v221
	s_nop 0
	v_cndmask_b32_e32 v57, v238, v57, vcc
	v_cmp_le_i32_e32 vcc, v14, v227
	v_or_b32_e32 v14, 0xf2, v221
	s_nop 0
	v_cndmask_b32_e32 v74, v238, v82, vcc
	v_cmp_le_i32_e32 vcc, v14, v227
	v_or_b32_e32 v14, 0xd3, v221
	s_nop 0
	v_cndmask_b32_e32 v58, v238, v58, vcc
	v_cmp_le_i32_e32 vcc, v14, v227
	v_or_b32_e32 v14, 0xf3, v221
	s_nop 0
	v_cndmask_b32_e32 v75, v238, v83, vcc
	v_cmp_le_i32_e32 vcc, v14, v227
	v_or_b32_e32 v14, 0xd8, v221
	v_max3_f32 v15, v15, v74, v75
	v_cndmask_b32_e32 v59, v238, v59, vcc
	v_cmp_le_i32_e32 vcc, v14, v227
	v_or_b32_e32 v14, 0xf8, v221
	v_max3_f32 v15, v15, v58, v59
	v_cndmask_b32_e32 v76, v238, v88, vcc
	v_cmp_le_i32_e32 vcc, v14, v227
	v_or_b32_e32 v14, 0xd9, v221
	s_nop 0
	v_cndmask_b32_e32 v60, v238, v60, vcc
	v_cmp_le_i32_e32 vcc, v14, v227
	v_or_b32_e32 v14, 0xf9, v221
	s_nop 0
	v_cndmask_b32_e32 v77, v238, v89, vcc
	v_cmp_le_i32_e32 vcc, v14, v227
	v_or_b32_e32 v14, 0xda, v221
	s_nop 0
	v_cndmask_b32_e32 v61, v238, v61, vcc
	v_cmp_le_i32_e32 vcc, v14, v227
	v_or_b32_e32 v14, 0xfa, v221
	s_nop 0
	v_cndmask_b32_e32 v78, v238, v90, vcc
	v_cmp_le_i32_e32 vcc, v14, v227
	v_or_b32_e32 v14, 0xdb, v221
	s_nop 0
	v_cndmask_b32_e32 v62, v238, v62, vcc
	v_cmp_le_i32_e32 vcc, v14, v227
	v_or_b32_e32 v14, 0xfb, v221
	s_nop 0
	v_cndmask_b32_e32 v79, v238, v91, vcc
	v_cmp_le_i32_e32 vcc, v14, v227
	v_max_f32_e32 v14, v64, v65
	v_max3_f32 v14, v14, v48, v50
	v_max3_f32 v14, v14, v51, v68
	v_max3_f32 v14, v14, v69, v52
	v_max3_f32 v14, v14, v53, v72
	v_max3_f32 v14, v14, v73, v56
	v_cndmask_b32_e32 v63, v238, v63, vcc
	v_max3_f32 v14, v14, v57, v76
	v_max3_f32 v15, v15, v78, v79
	v_max3_f32 v14, v14, v77, v60
	v_max3_f32 v15, v15, v62, v63
	v_max3_f32 v14, v14, v61, v15
	v_mov_b32_e32 v15, v14
	s_nop 1
	v_permlane32_swap_b32_e32 v14, v15
	v_max_f32_e32 v15, v15, v15
	v_max_f32_e32 v14, v14, v14
	v_max_f32_e32 v14, v14, v15
	v_cmp_lt_f32_e32 vcc, s36, v14
	s_cmp_lg_u64 vcc, 0
	s_cselect_b64 s[2:3], -1, 0
	s_cbranch_vccnz .LBB0_1395
.LBB0_1383:
	v_mfma_f32_32x32x16_bf16 v[32:47], v[156:159], v[6:9], v[32:47]
	v_exp_f32_e32 v64, v64
	v_exp_f32_e32 v65, v65
	v_exp_f32_e32 v66, v66
	v_exp_f32_e32 v67, v67
	v_mfma_f32_32x32x16_bf16 v[16:31], v[156:159], v[2:5], v[16:31]
	v_exp_f32_e32 v68, v68
	v_exp_f32_e32 v69, v69
	v_exp_f32_e32 v70, v70
	v_exp_f32_e32 v71, v71
	v_mfma_f32_32x32x16_bf16 v[32:47], v[152:155], v[10:13], v[32:47]
	v_exp_f32_e32 v72, v72
	v_exp_f32_e32 v73, v73
	v_exp_f32_e32 v74, v74
	v_exp_f32_e32 v75, v75
	v_mfma_f32_32x32x16_bf16 v[16:31], v[152:155], v[112:115], v[16:31]
	v_exp_f32_e32 v76, v76
	v_exp_f32_e32 v77, v77
	v_exp_f32_e32 v78, v78
	v_exp_f32_e32 v79, v79
	v_mfma_f32_32x32x16_bf16 v[32:47], v[148:151], v[116:119], v[32:47]
	v_exp_f32_e32 v48, v48
	v_exp_f32_e32 v49, v49
	v_exp_f32_e32 v50, v50
	v_exp_f32_e32 v51, v51
	v_mfma_f32_32x32x16_bf16 v[16:31], v[148:151], v[120:123], v[16:31]
	v_exp_f32_e32 v52, v52
	v_exp_f32_e32 v53, v53
	v_exp_f32_e32 v54, v54
	v_exp_f32_e32 v55, v55
	v_mfma_f32_32x32x16_bf16 v[32:47], v[144:147], v[124:127], v[32:47]
	v_exp_f32_e32 v56, v56
	v_exp_f32_e32 v57, v57
	v_exp_f32_e32 v58, v58
	v_exp_f32_e32 v59, v59
	v_mfma_f32_32x32x16_bf16 v[16:31], v[144:147], v[132:135], v[16:31]
	v_exp_f32_e32 v60, v60
	v_exp_f32_e32 v61, v61
	v_exp_f32_e32 v62, v62
	v_exp_f32_e32 v63, v63
	s_andn2_b64 vcc, exec, s[2:3]
	s_cbranch_vccnz .LBB0_1385
	s_waitcnt lgkmcnt(0)
	ds_read_b128 v[2:5], v224 offset:49248
	ds_read_b128 v[6:9], v224 offset:49216
	ds_read_b128 v[10:13], v224 offset:49184
	ds_read_b128 v[80:83], v224 offset:49152
	s_waitcnt lgkmcnt(3)
	v_mul_f32_e32 v46, v46, v4
	v_mul_f32_e32 v47, v47, v5
	s_waitcnt lgkmcnt(2)
	v_mul_f32_e32 v42, v42, v8
	v_mul_f32_e32 v43, v43, v9
	s_waitcnt lgkmcnt(1)
	v_mul_f32_e32 v38, v38, v12
	v_mul_f32_e32 v39, v39, v13
	s_waitcnt lgkmcnt(0)
	v_mul_f32_e32 v34, v34, v82
	v_mul_f32_e32 v35, v35, v83
	v_mul_f32_e32 v44, v44, v2
	v_mul_f32_e32 v45, v45, v3
	v_mul_f32_e32 v40, v40, v6
	v_mul_f32_e32 v41, v41, v7
	v_mul_f32_e32 v36, v36, v10
	v_mul_f32_e32 v37, v37, v11
	v_mul_f32_e32 v32, v32, v80
	v_mul_f32_e32 v33, v33, v81
	v_mul_f32_e32 v30, v30, v4
	v_mul_f32_e32 v31, v31, v5
	v_mul_f32_e32 v26, v26, v8
	v_mul_f32_e32 v27, v27, v9
	v_mul_f32_e32 v22, v22, v12
	v_mul_f32_e32 v23, v23, v13
	v_mul_f32_e32 v18, v18, v82
	v_mul_f32_e32 v19, v19, v83
	v_mul_f32_e32 v28, v28, v2
	v_mul_f32_e32 v29, v29, v3
	v_mul_f32_e32 v24, v24, v6
	v_mul_f32_e32 v25, v25, v7
	v_mul_f32_e32 v20, v20, v10
	v_mul_f32_e32 v21, v21, v11
	v_mul_f32_e32 v16, v16, v80
	v_mul_f32_e32 v17, v17, v81
